# HGRN c3: V^T staging lane mapping changed to spread LDS banks (16-way conflict on 16-bit transposition writes -> 4-way)
# speedup vs baseline: 1.0045x; 1.0034x over previous
; DEV void phase_hg_c3(const Params& p, char* smem) {
;     ...
;   for (int item = blockIdx.x; item < items; item += gridDim.x) {
;     const int c = item >> 4, bh = item & 15, b = bh >> 3, h = bh & 7;
;     const int cidx = c + 4;
;     const int r0 = b * 8192 + c * 64;
;     f32x4 acc[2][4];
; #pragma unroll
;     for (int i = 0; i < 2; i++)
; #pragma unroll
;       for (int j = 0; j < 4; j++) acc[i][j] = (f32x4){0.f, 0.f, 0.f, 0.f};
; #pragma unroll 1
;     for (int dir = 0; dir < 2; dir++) {
;       __syncthreads();
;       const int k = tid & 127, half = tid >> 7;
;       {
;         const bf16_t* lsrc = (dir ? LBp : LFp);
; #pragma unroll
;         for (int i = 0; i < 4; i++) {
;           int id = tid + i * 256; int s = id >> 4, cc = id & 15;
.LBB0_277:
	s_ashr_i32 s6, s20, 4
	s_lshl_b32 s14, s20, 10
	s_lshl_b32 s15, s6, 6
	s_and_b32 s14, s14, 0x2000
	s_and_b32 s7, s20, 15
	s_add_i32 s21, s14, s15
	s_lshl_b32 s14, s20, 7
	s_add_i32 s51, s6, 4
	s_and_b32 s14, s14, 0x380
	s_lshl_b32 s44, s7, 1
	v_add_u32_e32 v2, s21, v131
	s_cmp_gt_i32 s6, -1
	v_ashrrev_i32_e32 v3, 31, v2
	v_writelane_b32 v255, s20, 10
	v_or_b32_e32 v0, s14, v124
	s_cselect_b32 s6, 0x87, 3
	v_lshlrev_b64 v[84:85], 10, v[2:3]
	v_writelane_b32 v255, s14, 11
	s_sub_i32 s45, s6, s51
	v_or_b32_e32 v84, v84, v0
	v_readlane_b32 s14, v254, 58
	v_readlane_b32 s6, v254, 56
	v_lshlrev_b64 v[2:3], 1, v[84:85]
	v_readlane_b32 s15, v254, 59
	v_readlane_b32 s7, v254, 57
	s_mov_b32 s95, s21
	v_lshl_add_u64 v[86:87], s[14:15], 0, v[2:3]
	v_lshl_add_u64 v[88:89], s[6:7], 0, v[2:3]
	v_add_u32_e32 v2, s21, v135
	v_ashrrev_i32_e32 v3, 31, v2
	v_lshlrev_b64 v[90:91], 10, v[2:3]
	v_or_b32_e32 v90, v90, v0
	v_lshlrev_b64 v[2:3], 1, v[90:91]
	v_lshl_add_u64 v[92:93], s[14:15], 0, v[2:3]
	v_lshl_add_u64 v[94:95], s[6:7], 0, v[2:3]
	v_add_u32_e32 v2, s21, v139
	v_ashrrev_i32_e32 v3, 31, v2
	v_lshlrev_b64 v[96:97], 10, v[2:3]
	v_or_b32_e32 v96, v96, v0
	v_lshlrev_b64 v[2:3], 1, v[96:97]
	v_lshl_add_u64 v[98:99], s[14:15], 0, v[2:3]
	v_lshl_add_u64 v[100:101], s[6:7], 0, v[2:3]
	v_add_u32_e32 v2, s21, v143
	v_ashrrev_i32_e32 v3, 31, v2
	v_lshlrev_b64 v[102:103], 10, v[2:3]
	v_or_b32_e32 v102, v102, v0
	v_lshlrev_b64 v[2:3], 1, v[102:103]
	v_lshl_add_u64 v[104:105], s[14:15], 0, v[2:3]
	v_lshl_add_u64 v[106:107], s[6:7], 0, v[2:3]
	v_bfe_u32 v246, v195, 2, 4
	v_lshrrev_b32_e32 v247, 6, v195
	v_and_b32_e32 v248, 3, v195
	v_lshl_or_b32 v247, v247, 2, v248
	v_and_b32_e32 v248, 0x380, v0
	v_lshl_or_b32 v248, v247, 3, v248
	v_add_u32_e32 v2, s21, v246
	v_ashrrev_i32_e32 v3, 31, v2
	v_lshlrev_b64 v[2:3], 10, v[2:3]
	v_or_b32_e32 v2, v2, v248
	v_lshlrev_b64 v[2:3], 1, v[2:3]
	v_lshl_add_u64 v[244:245], s[14:15], 0, v[2:3]
	v_mov_b32_e32 v192, 0x8000
	v_mov_b32_e32 v193, 0
	v_mul_u32_u24_e32 v194, 0x500, v247
	v_lshl_add_u32 v194, v246, 1, v194
	v_mov_b32_e32 v2, 0
	s_mov_b32 s20, 0
	s_mov_b64 s[6:7], -1
	v_mov_b32_e32 v3, v2
	v_mov_b32_e32 v4, v2
	v_mov_b32_e32 v5, v2
	v_mov_b32_e32 v6, v2
	v_mov_b32_e32 v7, v2
	v_mov_b32_e32 v8, v2
	v_mov_b32_e32 v9, v2
	v_mov_b32_e32 v10, v2
	v_mov_b32_e32 v11, v2
	v_mov_b32_e32 v12, v2
	v_mov_b32_e32 v13, v2
	v_mov_b32_e32 v14, v2
	v_mov_b32_e32 v15, v2
	v_mov_b32_e32 v16, v2
	v_mov_b32_e32 v17, v2
	v_mov_b32_e32 v18, v2
	v_mov_b32_e32 v19, v2
	v_mov_b32_e32 v20, v2
	v_mov_b32_e32 v21, v2
	s_waitcnt vmcnt(21)
	v_mov_b32_e32 v22, v2
	v_mov_b32_e32 v23, v2
	v_mov_b32_e32 v24, v2
	v_mov_b32_e32 v25, v2
	v_mov_b32_e32 v26, v2
	v_mov_b32_e32 v27, v2
	v_mov_b32_e32 v28, v2
	v_mov_b32_e32 v29, v2
	s_waitcnt vmcnt(20)
	v_mov_b32_e32 v30, v2
	v_mov_b32_e32 v31, v2
	v_mov_b32_e32 v32, v2
	v_mov_b32_e32 v33, v2
	s_branch .LBB0_279

; DEV void phase_hg_c3(const Params& p, char* smem) {
;     ...
;       __syncthreads();
;       const int k = tid & 127, half = tid >> 7;
;       {
;         const bf16_t* lsrc = (dir ? LBp : LFp);
; #pragma unroll
;         for (int i = 0; i < 4; i++) {
;           int id = tid + i * 256; int s = id >> 4, cc = id & 15;
;           const size_t go = (size_t)(r0 + s) * 1024 + h * 128 + cc * 8;
;           uint4 u = *(const uint4*)(IH + go);
;           *(uint4*)(Kin + s * 144 + cc * 8) = *(const uint4*)(lsrc + go);
;           *(uint4*)(Qin + s * 144 + cc * 8) = *(const uint4*)(QH + go);
;           bf16_t* vt = Vt + (cc * 8) * 80 + s;
;           vt[0] = (bf16_t)(u.x & 0xffff); vt[80] = (bf16_t)(u.x >> 16); vt[160] = (bf16_t)(u.y & 0xffff); vt[240] = (bf16_t)(u.y >> 16);
;           vt[320] = (bf16_t)(u.z & 0xffff); vt[400] = (bf16_t)(u.z >> 16); vt[480] = (bf16_t)(u.w & 0xffff); vt[560] = (bf16_t)(u.w >> 16);
;         }
.LBB0_279:
	s_xor_b64 s[78:79], s[6:7], -1
	s_and_b64 s[14:15], s[6:7], exec
	s_mov_b32 s14, 0xe400000
	s_cselect_b32 s14, s14, 0x10500000
	s_add_u32 s14, s28, s14
	s_addc_u32 s15, s29, 0
	s_waitcnt vmcnt(19)
	v_lshl_add_u64 v[38:39], v[84:85], 1, s[14:15]
	v_lshl_add_u64 v[42:43], v[90:91], 1, s[14:15]
	v_lshl_add_u64 v[46:47], v[96:97], 1, s[14:15]
	v_lshl_add_u64 v[50:51], v[102:103], 1, s[14:15]
	v_lshl_add_u64 v[176:177], v[192:193], 0, v[244:245]
	v_lshl_add_u64 v[184:185], v[192:193], 1, v[244:245]
	v_lshl_add_u64 v[236:237], v[192:193], 0, v[184:185]
	s_waitcnt lgkmcnt(0)
	s_barrier
	global_load_dwordx4 v[38:41], v[38:39], off
	global_load_dwordx4 v[34:37], v[244:245], off
	global_load_dwordx4 v[172:175], v[88:89], off
	global_load_dwordx4 v[42:45], v[42:43], off
	global_load_dwordx4 v[176:179], v[176:177], off
	global_load_dwordx4 v[180:183], v[94:95], off
	global_load_dwordx4 v[46:49], v[46:47], off
	global_load_dwordx4 v[184:187], v[184:185], off
	global_load_dwordx4 v[188:191], v[100:101], off
	global_load_dwordx4 v[50:53], v[50:51], off
	global_load_dwordx4 v[236:239], v[236:237], off
	global_load_dwordx4 v[240:243], v[106:107], off
	s_waitcnt vmcnt(11)
	ds_write_b128 v133, v[38:41]
	s_waitcnt vmcnt(10)
	ds_write_b16 v194, v34 offset:36864
	ds_write_b16_d16_hi v194, v34 offset:37024
	ds_write_b16 v194, v35 offset:37184
	ds_write_b16_d16_hi v194, v35 offset:37344
	ds_write_b16 v194, v36 offset:37504
	ds_write_b16_d16_hi v194, v36 offset:37664
	ds_write_b16 v194, v37 offset:37824
	ds_write_b16_d16_hi v194, v37 offset:37984
	s_waitcnt vmcnt(9)
	ds_write_b128 v132, v[172:175]
	s_waitcnt vmcnt(8)
	ds_write_b128 v137, v[42:45]
	s_waitcnt vmcnt(7)
	ds_write_b16 v194, v176 offset:36896
	ds_write_b16_d16_hi v194, v176 offset:37056
	ds_write_b16 v194, v177 offset:37216
	ds_write_b16_d16_hi v194, v177 offset:37376
	ds_write_b16 v194, v178 offset:37536
	ds_write_b16_d16_hi v194, v178 offset:37696
	ds_write_b16 v194, v179 offset:37856
	ds_write_b16_d16_hi v194, v179 offset:38016
	s_waitcnt vmcnt(6)
	ds_write_b128 v136, v[180:183]
	s_waitcnt vmcnt(5)
	ds_write_b128 v141, v[46:49]
	s_waitcnt vmcnt(4)
	ds_write_b16 v194, v184 offset:36928
	ds_write_b16_d16_hi v194, v184 offset:37088
	ds_write_b16 v194, v185 offset:37248
	ds_write_b16_d16_hi v194, v185 offset:37408
	ds_write_b16 v194, v186 offset:37568
	ds_write_b16_d16_hi v194, v186 offset:37728
	ds_write_b16 v194, v187 offset:37888
	ds_write_b16_d16_hi v194, v187 offset:38048
	s_waitcnt vmcnt(3)
	ds_write_b128 v140, v[188:191]
	s_waitcnt vmcnt(2)
	ds_write_b128 v145, v[50:53]
	s_waitcnt vmcnt(1)
	ds_write_b16 v194, v236 offset:36960
	ds_write_b16_d16_hi v194, v236 offset:37120
	ds_write_b16 v194, v237 offset:37280
	ds_write_b16_d16_hi v194, v237 offset:37440
	ds_write_b16 v194, v238 offset:37600
	ds_write_b16_d16_hi v194, v238 offset:37760
	ds_write_b16 v194, v239 offset:37920
	ds_write_b16_d16_hi v194, v239 offset:38080
	s_waitcnt vmcnt(0)
	ds_write_b128 v144, v[240:243]
	v_mov_b32_e32 v0, 0
	s_or_b32 s14, s20, s44
	s_and_b64 s[6:7], s[6:7], exec
	s_cselect_b32 s6, s51, s45
	s_mulk_i32 s14, 0x84
	s_ashr_i32 s7, s6, 31
	s_add_u32 s6, s14, s6
	s_addc_u32 s7, 0, s7
	s_lshl_b64 s[6:7], s[6:7], 15
	v_lshl_add_u64 v[62:63], v[66:67], 0, s[6:7]
	v_lshl_add_u64 v[42:43], v[72:73], 1, v[62:63]
	v_lshl_add_u64 v[46:47], v[74:75], 1, v[62:63]
	v_lshl_add_u64 v[50:51], v[76:77], 1, v[62:63]
	v_lshl_add_u64 v[54:55], v[78:79], 1, v[62:63]
	v_lshl_add_u64 v[58:59], v[80:81], 1, v[62:63]
	s_mov_b32 s6, 0
	v_lshl_add_u64 v[34:35], v[68:69], 1, v[62:63]
	v_lshl_add_u64 v[38:39], v[70:71], 1, v[62:63]
	v_lshl_add_u64 v[62:63], v[82:83], 1, v[62:63]
	global_load_dwordx4 v[34:37], v[34:35], off
	s_nop 0
	global_load_dwordx4 v[38:41], v[38:39], off
	s_nop 0
	global_load_dwordx4 v[42:45], v[42:43], off
	s_nop 0
	global_load_dwordx4 v[46:49], v[46:47], off
	s_nop 0
	global_load_dwordx4 v[50:53], v[50:51], off
	s_nop 0
	global_load_dwordx4 v[54:57], v[54:55], off
	s_nop 0
	global_load_dwordx4 v[58:61], v[58:59], off
	s_nop 0
	global_load_dwordx4 v[62:65], v[62:63], off
	s_waitcnt lgkmcnt(0)
	s_barrier
